# attention: no s_nop 7 between QK and the fast softmax (first VALU reads only old accumulators); tile 0 goes straight to the max-tracking softmax instead of fast path + QK recompute
# speedup vs baseline: 1.0056x; 1.0056x over previous
.Lat_v2skip:
	ds_read_b128 v[208:211], v173 offset:18432
	s_waitcnt lgkmcnt(1)
	v_mfma_f32_16x16x32_bf16 v[140:143], v[204:207], v[104:107], 0
	v_mfma_f32_16x16x32_bf16 v[132:135], v[204:207], v[108:111], 0
	ds_read_b128 v[204:207], v175 offset:18432
	s_waitcnt lgkmcnt(1)
	v_mfma_f32_16x16x32_bf16 v[140:143], v[208:211], v[96:99], v[140:143]
	v_mfma_f32_16x16x32_bf16 v[132:135], v[208:211], v[100:103], v[132:135]
	ds_read_b128 v[208:211], v177 offset:18432
	s_waitcnt lgkmcnt(1)
	v_mfma_f32_16x16x32_bf16 v[140:143], v[204:207], v[88:91], v[140:143]
	v_mfma_f32_16x16x32_bf16 v[132:135], v[204:207], v[92:95], v[132:135]
	ds_read_b128 v[204:207], v179 offset:18432
	s_waitcnt lgkmcnt(1)
	v_mfma_f32_16x16x32_bf16 v[140:143], v[208:211], v[80:83], v[140:143]
	v_mfma_f32_16x16x32_bf16 v[132:135], v[208:211], v[84:87], v[132:135]
	ds_read_b128 v[208:211], v195 offset:18432
	s_waitcnt lgkmcnt(1)
	v_mfma_f32_16x16x32_bf16 v[140:143], v[204:207], v[72:75], v[140:143]
	v_mfma_f32_16x16x32_bf16 v[132:135], v[204:207], v[76:79], v[132:135]
	s_waitcnt lgkmcnt(0)
	v_mfma_f32_16x16x32_bf16 v[140:143], v[208:211], v[64:67], v[140:143]
	v_mfma_f32_16x16x32_bf16 v[132:135], v[208:211], v[68:71], v[132:135]
	s_cmp_eq_u32 s29, 0
	s_cbranch_scc1 .Lattn_slow_sm
	v_fmamk_f32 v112, v112, 0x3dd53b94, v157
	v_fmamk_f32 v113, v113, 0x3dd53b94, v157
	v_fmamk_f32 v114, v114, 0x3dd53b94, v157
	v_exp_f32_e32 v112, v112
	v_fmamk_f32 v115, v115, 0x3dd53b94, v157
	v_exp_f32_e32 v113, v113
	v_fmamk_f32 v116, v116, 0x3dd53b94, v157
	v_exp_f32_e32 v114, v114
	v_fmamk_f32 v117, v117, 0x3dd53b94, v157
	v_exp_f32_e32 v115, v115
	v_fmamk_f32 v118, v118, 0x3dd53b94, v157
	v_exp_f32_e32 v116, v116
	v_fmamk_f32 v119, v119, 0x3dd53b94, v157
	v_exp_f32_e32 v117, v117
	v_fmamk_f32 v136, v136, 0x3dd53b94, v157
	v_exp_f32_e32 v118, v118
	v_fmamk_f32 v137, v137, 0x3dd53b94, v157
	v_exp_f32_e32 v119, v119
	v_fmamk_f32 v138, v138, 0x3dd53b94, v157
	v_exp_f32_e32 v136, v136
	v_fmamk_f32 v139, v139, 0x3dd53b94, v157
	v_exp_f32_e32 v137, v137
	v_fmamk_f32 v140, v140, 0x3dd53b94, v157
	v_exp_f32_e32 v138, v138
	v_fmamk_f32 v141, v141, 0x3dd53b94, v157
	v_exp_f32_e32 v139, v139
	v_fmamk_f32 v142, v142, 0x3dd53b94, v157
	v_exp_f32_e32 v140, v140
	v_fmamk_f32 v143, v143, 0x3dd53b94, v157
	v_exp_f32_e32 v141, v141
	v_exp_f32_e32 v142, v142
	v_exp_f32_e32 v143, v143
	s_nop 0
	v_add_f32_e32 v204, v112, v113
	v_add_f32_e32 v205, v114, v115
	v_add_f32_e32 v206, v116, v117
	v_add_f32_e32 v207, v118, v119
	v_add_f32_e32 v208, v136, v137
	v_add_f32_e32 v209, v138, v139
	v_add_f32_e32 v210, v140, v141
	v_add_f32_e32 v211, v142, v143
	v_add_f32_e32 v204, v204, v205
	v_add_f32_e32 v206, v206, v207
	v_add_f32_e32 v208, v208, v209
	v_add_f32_e32 v210, v210, v211
	v_add_f32_e32 v204, v204, v206
	v_add_f32_e32 v208, v208, v210
	v_add_f32_e32 v195, v204, v208
	v_fmamk_f32 v120, v120, 0x3dd53b94, v155
	v_fmamk_f32 v121, v121, 0x3dd53b94, v155
	v_fmamk_f32 v122, v122, 0x3dd53b94, v155
	v_exp_f32_e32 v120, v120
	v_fmamk_f32 v123, v123, 0x3dd53b94, v155
	v_exp_f32_e32 v121, v121
	v_fmamk_f32 v124, v124, 0x3dd53b94, v155
	v_exp_f32_e32 v122, v122
	v_fmamk_f32 v125, v125, 0x3dd53b94, v155
	v_exp_f32_e32 v123, v123
	v_fmamk_f32 v126, v126, 0x3dd53b94, v155
	v_exp_f32_e32 v124, v124
	v_fmamk_f32 v127, v127, 0x3dd53b94, v155
	v_exp_f32_e32 v125, v125
	v_fmamk_f32 v128, v128, 0x3dd53b94, v155
	v_exp_f32_e32 v126, v126
	v_fmamk_f32 v129, v129, 0x3dd53b94, v155
	v_exp_f32_e32 v127, v127
	v_fmamk_f32 v130, v130, 0x3dd53b94, v155
	v_exp_f32_e32 v128, v128
	v_fmamk_f32 v131, v131, 0x3dd53b94, v155
	v_exp_f32_e32 v129, v129
	v_fmamk_f32 v132, v132, 0x3dd53b94, v155
	v_exp_f32_e32 v130, v130
	v_fmamk_f32 v133, v133, 0x3dd53b94, v155
	v_exp_f32_e32 v131, v131
	v_fmamk_f32 v134, v134, 0x3dd53b94, v155
	v_exp_f32_e32 v132, v132
	v_fmamk_f32 v135, v135, 0x3dd53b94, v155
	v_exp_f32_e32 v133, v133
	v_exp_f32_e32 v134, v134
	v_exp_f32_e32 v135, v135
	s_nop 0
	v_add_f32_e32 v204, v120, v121
	v_add_f32_e32 v205, v122, v123
	v_add_f32_e32 v206, v124, v125
	v_add_f32_e32 v207, v126, v127
	v_add_f32_e32 v208, v128, v129
	v_add_f32_e32 v209, v130, v131
	v_add_f32_e32 v210, v132, v133
	v_add_f32_e32 v211, v134, v135
	v_add_f32_e32 v204, v204, v205
	v_add_f32_e32 v206, v206, v207
	v_add_f32_e32 v208, v208, v209
	v_add_f32_e32 v210, v210, v211
	v_add_f32_e32 v204, v204, v206
	v_add_f32_e32 v208, v208, v210
	v_add_f32_e32 v230, v204, v208
	v_add_f32_e32 v211, v195, v230
	v_cmp_ge_f32_e32 vcc, 0x47800000, v211
	s_cmp_eq_u64 vcc, exec
	s_cbranch_scc0 .Lattn_slow
	v_add_f32_e32 v156, v156, v195
	v_add_f32_e32 v154, v154, v230
	v_cvt_pk_bf16_f32 v119, v118, v119
	v_cvt_pk_bf16_f32 v118, v116, v117
	v_cvt_pk_bf16_f32 v116, v112, v113
	v_cvt_pk_bf16_f32 v117, v114, v115
	v_cvt_pk_bf16_f32 v112, v136, v137
	v_cvt_pk_bf16_f32 v113, v138, v139
	v_cvt_pk_bf16_f32 v114, v140, v141
	v_cvt_pk_bf16_f32 v115, v142, v143
	v_cvt_pk_bf16_f32 v127, v126, v127
	v_cvt_pk_bf16_f32 v126, v124, v125
	v_cvt_pk_bf16_f32 v124, v120, v121
	v_cvt_pk_bf16_f32 v125, v122, v123
	v_cvt_pk_bf16_f32 v120, v128, v129
	v_cvt_pk_bf16_f32 v121, v130, v131
	v_cvt_pk_bf16_f32 v122, v132, v133
	v_cvt_pk_bf16_f32 v123, v134, v135

.Lattn_slow_sm:
	s_nop 7
	v_max_f32_e32 v157, v112, v112
	v_max_f32_e32 v195, v114, v114
	v_max_f32_e32 v155, v113, v113
	v_max_f32_e32 v155, v157, v155
	v_max_f32_e32 v157, v115, v115
	v_max_f32_e32 v157, v195, v157
	v_max_f32_e32 v195, v119, v119
	v_max_f32_e32 v204, v118, v118
	v_max_f32_e32 v195, v204, v195
	v_max3_f32 v195, v116, v117, v195
	v_max3_f32 v155, v155, v157, v195
	v_max_f32_e32 v157, v139, v139
	v_max_f32_e32 v195, v138, v138
	v_max_f32_e32 v157, v195, v157
	v_max_f32_e32 v195, v143, v143
	v_max_f32_e32 v204, v142, v142
	v_max_f32_e32 v195, v204, v195
	v_max3_f32 v157, v136, v137, v157
	v_max3_f32 v195, v140, v141, v195
	v_max3_f32 v155, v155, v157, v195
	v_sub_f32_e32 v157, v155, v162
	v_cmp_ge_f32_e32 vcc, s89, v157
	s_cmp_eq_u64 vcc, exec
	s_cbranch_scc1 .LBB0_1005
	v_and_b32_e32 v195, 64, v227
	v_xor_b32_e32 v157, 16, v227
	v_add_u32_e32 v195, 64, v195
	v_cmp_lt_i32_e32 vcc, v157, v195
	s_nop 1
	v_cndmask_b32_e32 v157, v227, v157, vcc
	v_lshlrev_b32_e32 v157, 2, v157
	ds_bpermute_b32 v157, v157, v155
	v_max_f32_e32 v155, v155, v155
	s_waitcnt lgkmcnt(0)
	v_max_f32_e32 v157, v157, v157
	v_max_f32_e32 v155, v155, v157
	v_xor_b32_e32 v157, 32, v227
	v_cmp_lt_i32_e32 vcc, v157, v195
	s_nop 1
	v_cndmask_b32_e32 v157, v227, v157, vcc
	v_lshlrev_b32_e32 v157, 2, v157
	ds_bpermute_b32 v157, v157, v155
	s_waitcnt lgkmcnt(0)
	v_max3_f32 v155, v162, v155, v157
	v_sub_f32_e32 v157, v162, v155
	v_mul_f32_e32 v157, 0x3dd53b94, v157
	v_exp_f32_e32 v162, v157
	s_nop 0
	v_mul_f32_e32 v156, v156, v162
	v_pk_mul_f32 v[62:63], v[62:63], v[162:163] op_sel_hi:[1,0]
	v_pk_mul_f32 v[60:61], v[60:61], v[162:163] op_sel_hi:[1,0]
	v_pk_mul_f32 v[54:55], v[54:55], v[162:163] op_sel_hi:[1,0]
	v_pk_mul_f32 v[52:53], v[52:53], v[162:163] op_sel_hi:[1,0]
	v_pk_mul_f32 v[46:47], v[46:47], v[162:163] op_sel_hi:[1,0]
	v_pk_mul_f32 v[44:45], v[44:45], v[162:163] op_sel_hi:[1,0]
	v_pk_mul_f32 v[38:39], v[38:39], v[162:163] op_sel_hi:[1,0]
	v_pk_mul_f32 v[36:37], v[36:37], v[162:163] op_sel_hi:[1,0]
	v_pk_mul_f32 v[26:27], v[26:27], v[162:163] op_sel_hi:[1,0]
	v_pk_mul_f32 v[24:25], v[24:25], v[162:163] op_sel_hi:[1,0]
	v_pk_mul_f32 v[18:19], v[18:19], v[162:163] op_sel_hi:[1,0]
	v_pk_mul_f32 v[16:17], v[16:17], v[162:163] op_sel_hi:[1,0]
	v_pk_mul_f32 v[10:11], v[10:11], v[162:163] op_sel_hi:[1,0]
	v_pk_mul_f32 v[8:9], v[8:9], v[162:163] op_sel_hi:[1,0]
	v_pk_mul_f32 v[2:3], v[2:3], v[162:163] op_sel_hi:[1,0]
	v_pk_mul_f32 v[0:1], v[0:1], v[162:163] op_sel_hi:[1,0]
	v_mov_b32_e32 v162, v155
